# one static s_setprio 1 for waves 4-7 across the prompt-attention tile loop (reset after the loop)
# baseline (speedup 1.0000x reference)
;     ...
;     auto lstore = [&](int buf) { bf16_t* Kb = (bf16_t*)(lds + buf * BUFB); bf16_t* Vb = (bf16_t*)(lds + buf * BUFB + 64 * KSTR * 2);
; #pragma unroll
;         for (int i = 0; i < NKC; ++i) { const int e = tid + 512 * i, row = e / CPR, cc = e % CPR; *(u32x4*)(Kb + row * KSTR + 8 * cc) = kreg[i]; }
; #pragma unroll
;         for (int i = 0; i < 2; ++i) { const int e = tid + 512 * i, d = e >> 3, cc = e & 7; u32x2* q = (u32x2*)(Vb + d * VSTR + 8 * cc); q[0] = (u32x2){vreg[i].x, vreg[i].y}; q[1] = (u32x2){vreg[i].z, vreg[i].w}; } };
;     ...
;         gload(0); lstore(0); if (ntiles > 1) gload(1);
;         __syncthreads();
;         for (int t = 0; t < ntiles; ++t) { const int cur = t & 1;
;             if (t + 1 < ntiles) lstore(cur ^ 1);
;             if (t + 2 < ntiles) gload(t + 2);
.LBB0_1906:
	s_lshl_b32 s0, s15, 2
	v_ashrrev_i32_e32 v185, 31, v184
	v_mul_u32_u24_e32 v14, 0x88, v208
	s_add_i32 s13, s13, 5
	s_add_i32 s46, s16, 0x80
	s_sub_i32 s15, 0, s0
	s_movk_i32 s16, 0xff80
	s_waitcnt lgkmcnt(0)
	s_barrier
	s_sub_i32 s0, s13, s12
	s_cmp_le_i32 s0, 2
	s_cbranch_scc0 .Lprio_skip
	s_setprio 1
.Lprio_skip:
.LBB0_1907:
	s_add_i32 s18, s16, 0x81
	s_and_b32 s17, s18, 1
	s_add_i32 s0, s16, 0x82
	s_cmp_ge_u32 s0, s13
	s_cbranch_scc1 .LBB0_1913
	s_xor_b32 s0, s17, 1
	s_mul_i32 s0, s0, 0xa800
	s_add_i32 s0, s0, 0
	v_add3_u32 v0, s0, v210, v211
	s_waitcnt vmcnt(4)
	ds_write_b128 v0, v[160:163]
	v_add3_u32 v0, s0, v216, v217
	s_waitcnt vmcnt(3)
	ds_write_b128 v0, v[164:167]
	v_add3_u32 v0, s0, v218, v219
	s_waitcnt vmcnt(2)
	ds_write_b128 v0, v[168:171]
	v_lshl_add_u32 v0, v220, 1, s0
	v_add3_u32 v0, v0, v188, s89
	s_waitcnt vmcnt(1)
	ds_write2_b64 v0, v[172:173], v[174:175] offset1:1
	v_lshl_add_u32 v0, v221, 1, s0
	v_add3_u32 v0, v0, v188, s89
	s_waitcnt vmcnt(0)
	ds_write2_b64 v0, v[176:177], v[178:179] offset1:1
	s_add_i32 s0, s16, 0x83
	s_cmp_ge_u32 s0, s13
	s_cbranch_scc0 .LBB0_1914

; DI unsigned pk2(float lo, float hi) { f32x2 v = {lo, hi}; bf16x2_t b = __builtin_convertvector(v, bf16x2_t); return __builtin_bit_cast(unsigned, b); }
; DI float xhalf_sum(float v) { const auto r = __builtin_amdgcn_permlane32_swap(__float_as_uint(v), __float_as_uint(v), false, false); return __uint_as_float(r[0]) + __uint_as_float(r[1]); }
;     ...
;     const float lt = xhalf_sum(lrun), inv = 1.f / lt;
;     if (store) {
; #pragma unroll
;         for (int d = 0; d < 4; ++d)
; #pragma unroll
;             for (int g = 0; g < 4; ++g) { u32x2 w; w.x = pk2(oacc[d][4 * g] * inv, oacc[d][4 * g + 1] * inv); w.y = pk2(oacc[d][4 * g + 2] * inv, oacc[d][4 * g + 3] * inv); *(u32x2*)(orow + 32 * d + 8 * g + 4 * hi) = w; }
;     }
;     __syncthreads();
.LBB0_1930:
	s_setprio 0
	v_mov_b32_e32 v0, v223
	s_nop 1
	v_permlane32_swap_b32_e32 v223, v0
	v_add_f32_e32 v0, v223, v0
	v_div_scale_f32 v4, s[0:1], v0, v0, 1.0
	v_rcp_f32_e32 v5, v4
	v_lshlrev_b64 v[2:3], 11, v[184:185]
	v_lshl_add_u64 v[2:3], s[90:91], 0, v[2:3]
	s_lshl_b32 s46, s14, 1
	v_fma_f32 v6, -v4, v5, 1.0
	v_fmac_f32_e32 v5, v6, v5
	v_div_scale_f32 v6, vcc, 1.0, v0, 1.0
	v_mul_f32_e32 v7, v6, v5
	v_fma_f32 v8, -v4, v7, v6
	v_fmac_f32_e32 v7, v8, v5
	v_fma_f32 v4, -v4, v7, v6
	v_div_fmas_f32 v4, v4, v5, v7
	v_div_fixup_f32 v0, v4, v0, 1.0
	v_lshl_add_u64 v[2:3], v[2:3], 0, s[46:47]
	v_ashrrev_i32_e32 v201, 31, v200
	v_pk_mul_f32 v[4:5], v[32:33], v[0:1] op_sel_hi:[1,0]
	v_pk_mul_f32 v[6:7], v[34:35], v[0:1] op_sel_hi:[1,0]
	v_lshl_add_u64 v[2:3], v[200:201], 1, v[2:3]
	v_cvt_pk_bf16_f32 v4, v4, v5
	v_cvt_pk_bf16_f32 v5, v6, v7
	global_store_dwordx2 v[2:3], v[4:5], off offset:1024
	v_pk_mul_f32 v[4:5], v[36:37], v[0:1] op_sel_hi:[1,0]
	v_pk_mul_f32 v[6:7], v[38:39], v[0:1] op_sel_hi:[1,0]
	v_cvt_pk_bf16_f32 v4, v4, v5
	v_cvt_pk_bf16_f32 v5, v6, v7
	global_store_dwordx2 v[2:3], v[4:5], off offset:1040
	v_pk_mul_f32 v[4:5], v[40:41], v[0:1] op_sel_hi:[1,0]
	v_pk_mul_f32 v[6:7], v[42:43], v[0:1] op_sel_hi:[1,0]
	v_cvt_pk_bf16_f32 v4, v4, v5
	v_cvt_pk_bf16_f32 v5, v6, v7
	global_store_dwordx2 v[2:3], v[4:5], off offset:1056
	v_pk_mul_f32 v[4:5], v[44:45], v[0:1] op_sel_hi:[1,0]
	v_pk_mul_f32 v[6:7], v[46:47], v[0:1] op_sel_hi:[1,0]
	v_cvt_pk_bf16_f32 v4, v4, v5
	v_cvt_pk_bf16_f32 v5, v6, v7
	global_store_dwordx2 v[2:3], v[4:5], off offset:1072
	v_pk_mul_f32 v[4:5], v[64:65], v[0:1] op_sel_hi:[1,0]
	v_pk_mul_f32 v[6:7], v[66:67], v[0:1] op_sel_hi:[1,0]
	v_cvt_pk_bf16_f32 v4, v4, v5
	v_cvt_pk_bf16_f32 v5, v6, v7
	global_store_dwordx2 v[2:3], v[4:5], off offset:1088
	v_pk_mul_f32 v[4:5], v[68:69], v[0:1] op_sel_hi:[1,0]
	v_pk_mul_f32 v[6:7], v[70:71], v[0:1] op_sel_hi:[1,0]
	v_cvt_pk_bf16_f32 v4, v4, v5
	v_cvt_pk_bf16_f32 v5, v6, v7
	global_store_dwordx2 v[2:3], v[4:5], off offset:1104
	v_pk_mul_f32 v[4:5], v[72:73], v[0:1] op_sel_hi:[1,0]
	v_pk_mul_f32 v[6:7], v[74:75], v[0:1] op_sel_hi:[1,0]
	v_cvt_pk_bf16_f32 v4, v4, v5
	v_cvt_pk_bf16_f32 v5, v6, v7
	global_store_dwordx2 v[2:3], v[4:5], off offset:1120
	v_pk_mul_f32 v[4:5], v[76:77], v[0:1] op_sel_hi:[1,0]
	v_pk_mul_f32 v[6:7], v[78:79], v[0:1] op_sel_hi:[1,0]
	v_cvt_pk_bf16_f32 v4, v4, v5
	v_cvt_pk_bf16_f32 v5, v6, v7
	global_store_dwordx2 v[2:3], v[4:5], off offset:1136
	v_pk_mul_f32 v[4:5], v[48:49], v[0:1] op_sel_hi:[1,0]
	v_pk_mul_f32 v[6:7], v[50:51], v[0:1] op_sel_hi:[1,0]
	v_cvt_pk_bf16_f32 v4, v4, v5
	v_cvt_pk_bf16_f32 v5, v6, v7
	global_store_dwordx2 v[2:3], v[4:5], off offset:1152
	v_pk_mul_f32 v[4:5], v[52:53], v[0:1] op_sel_hi:[1,0]
	v_pk_mul_f32 v[6:7], v[54:55], v[0:1] op_sel_hi:[1,0]
	v_cvt_pk_bf16_f32 v4, v4, v5
	v_cvt_pk_bf16_f32 v5, v6, v7
	global_store_dwordx2 v[2:3], v[4:5], off offset:1168
	v_pk_mul_f32 v[4:5], v[56:57], v[0:1] op_sel_hi:[1,0]
	v_pk_mul_f32 v[6:7], v[58:59], v[0:1] op_sel_hi:[1,0]
	v_cvt_pk_bf16_f32 v4, v4, v5
	v_cvt_pk_bf16_f32 v5, v6, v7
	global_store_dwordx2 v[2:3], v[4:5], off offset:1184
	v_pk_mul_f32 v[4:5], v[60:61], v[0:1] op_sel_hi:[1,0]
	v_pk_mul_f32 v[6:7], v[62:63], v[0:1] op_sel_hi:[1,0]
	v_cvt_pk_bf16_f32 v4, v4, v5
	v_cvt_pk_bf16_f32 v5, v6, v7
	global_store_dwordx2 v[2:3], v[4:5], off offset:1200
	v_pk_mul_f32 v[4:5], v[16:17], v[0:1] op_sel_hi:[1,0]
	v_pk_mul_f32 v[6:7], v[18:19], v[0:1] op_sel_hi:[1,0]
	v_cvt_pk_bf16_f32 v4, v4, v5
	v_cvt_pk_bf16_f32 v5, v6, v7
	global_store_dwordx2 v[2:3], v[4:5], off offset:1216
	v_pk_mul_f32 v[4:5], v[20:21], v[0:1] op_sel_hi:[1,0]
	v_pk_mul_f32 v[6:7], v[22:23], v[0:1] op_sel_hi:[1,0]
	v_cvt_pk_bf16_f32 v4, v4, v5
	v_cvt_pk_bf16_f32 v5, v6, v7
	global_store_dwordx2 v[2:3], v[4:5], off offset:1232
	v_pk_mul_f32 v[4:5], v[24:25], v[0:1] op_sel_hi:[1,0]
	v_pk_mul_f32 v[6:7], v[26:27], v[0:1] op_sel_hi:[1,0]
	v_cvt_pk_bf16_f32 v4, v4, v5
	v_cvt_pk_bf16_f32 v5, v6, v7
	global_store_dwordx2 v[2:3], v[4:5], off offset:1248
	v_pk_mul_f32 v[4:5], v[28:29], v[0:1] op_sel_hi:[1,0]
	v_pk_mul_f32 v[6:7], v[30:31], v[0:1] op_sel_hi:[1,0]
	v_cvt_pk_bf16_f32 v4, v4, v5
	v_cvt_pk_bf16_f32 v5, v6, v7
	global_store_dwordx2 v[2:3], v[4:5], off offset:1264
	s_barrier
